# scan/A2 order swap per workgroup (blockIdx bit 7) instead of per wave half
# baseline (speedup 1.0000x reference)
; #define LAS __attribute__((address_space(3)))
; #define LAUNDER() int tp = TID0(); const int tid = tp, lane = tp & 63, wave = __builtin_amdgcn_readfirstlane(tp >> 6); (void)tid; (void)lane; (void)wave
; __global__ void __launch_bounds__(512) fwd_kernel(Args a) {
;     ...
;         if (IN(pb + 3) && EN_SCAN) { LAUNDER(); ssd_scan(STATES, TOT, blockIdx.x * 512 + tid, G * 512); }
;         if (IN(pb + 3) && EN_A) { LAUNDER(); LAS char* vt = (LAS char*)lds + wave * 16384;
;             for (int u = blockIdx.x; u < 512; u += G) { mixerA2_unit(u, PROJ, YC, LPA, KMAX + l * 1024, vt, wave, lane); } }
.Lsw_scan:
	s_cmp_eq_u32 s100, 0
	s_cbranch_scc0 .Lsw_doscan
	s_bitcmp1_b32 s66, 7
	s_cbranch_scc0 .Lsw_doscan
	s_mov_b32 s100, 1
	s_branch .Lsw_a2
